# st4->st5->st6 seams: 4-workgroup same-XCD arrive/poll barrier instead of the grid barrier (run-time XCC-id group check, grid-barrier fallback)
# speedup vs baseline: 1.0131x; 1.0120x over previous
_Z10hymba_mega6Paramsiii:
	s_mov_b32 s95, s2
	v_writelane_b32 v255, s0, 0
	v_writelane_b32 v255, 0, 60
	s_load_dwordx4 s[4:7], s[0:1], 0x128
	s_waitcnt lgkmcnt(0)
	s_cmp_lg_u32 s6, 0
	v_writelane_b32 v255, s1, 1
	s_cselect_b64 s[0:1], -1, 0
	v_writelane_b32 v255, s0, 2
	s_cmp_eq_u32 s6, 0
	s_nop 0
	v_writelane_b32 v255, s1, 3
	s_mov_b64 s[0:1], s[4:5]
	v_writelane_b32 v255, s0, 4
	s_nop 1
	v_writelane_b32 v255, s1, 5
	v_writelane_b32 v255, s2, 6
	v_writelane_b32 v255, s3, 7
	s_cbranch_scc1 .LBB0_7
	v_and_b32_e32 v1, 0x3ff, v0
	v_cmp_eq_u32_e32 vcc, 0, v1
	s_and_saveexec_b64 s[2:3], vcc
	s_cbranch_execz .LBB0_3
	s_add_i32 s0, 16, 0x26800
	v_mov_b32_e32 v2, 0
	v_mov_b32_e32 v3, v2
	v_mov_b32_e32 v4, v2
	v_mov_b32_e32 v5, v2
	v_mov_b32_e32 v1, s0
	ds_write_b128 v1, v[2:5]
.LBB0_3:
	s_or_b64 exec, exec, s[2:3]
	s_waitcnt lgkmcnt(0)
	s_barrier
	s_getreg_b32 s0, hwreg(HW_REG_XCC_ID, 0, 4)
	s_and_saveexec_b64 s[2:3], vcc
	s_cbranch_execz .LBB0_6
	s_mov_b64 s[4:5], exec
	v_mbcnt_lo_u32_b32 v1, s4, 0
	v_mbcnt_hi_u32_b32 v1, s5, v1
	v_cmp_eq_u32_e32 vcc, 0, v1
	s_and_b64 s[6:7], exec, vcc
	s_mov_b64 exec, s[6:7]
	s_cbranch_execz .LBB0_6
	v_readlane_b32 s6, v255, 0
	v_readlane_b32 s7, v255, 1
	s_load_dwordx2 s[6:7], s[6:7], 0x120
	s_and_b32 s8, s0, 15
	s_lshl_b32 s0, s0, 8
	s_and_b32 s0, s0, 0xf00
	s_bcnt1_i32_b64 s1, s[4:5]
	v_mov_b32_e32 v1, s0
	v_mov_b32_e32 v2, s1
	s_waitcnt lgkmcnt(0)
	global_atomic_add v1, v2, s[6:7] offset:1024
	s_and_b32 s9, s95, 7
	s_lshr_b32 s10, s95, 5
	s_lshl_b32 s10, s10, 3
	s_add_i32 s9, s9, s10
	s_lshl_b32 s9, s9, 3
	s_add_i32 s9, s9, 0xa000
	v_mov_b32_e32 v1, s9
	v_mov_b32_e32 v2, s8
	global_atomic_umax v1, v2, s[6:7] sc1
	s_sub_i32 s8, 15, s8
	v_mov_b32_e32 v2, s8
	global_atomic_umax v1, v2, s[6:7] offset:4 sc1

.LBB0_2018:
	s_add_i32 s0, s29, -1
	s_cmp_lt_i32 s0, 0
	s_cbranch_scc1 .Lgb_no
	s_mul_i32 s1, s0, 57
	s_lshr_b32 s1, s1, 9
	s_mul_i32 s2, s1, 9
	s_sub_i32 s2, s0, s2
	s_add_i32 s2, s2, -4
	s_cmp_gt_u32 s2, 1
	s_cbranch_scc1 .Lgb_no
	s_lshl_b32 s1, s1, 1
	s_add_i32 s1, s1, s2
	s_add_i32 s1, s1, 1
	s_lshl_b32 s1, s1, 2
	v_readlane_b32 s3, v255, 60
	s_cmp_lg_u32 s3, 0
	s_cbranch_scc1 .Lgb_known
	v_lshlrev_b32_e32 v0, 3, v191
	v_add_u32_e32 v0, 0xa000, v0
	global_load_dwordx2 v[0:1], v0, s[82:83] sc1
	s_waitcnt vmcnt(0)
	v_add_u32_e32 v0, v0, v1
	v_cmp_ne_u32_e32 vcc, 15, v0
	s_cmp_lg_u64 vcc, 0
	s_cselect_b32 s3, 2, 1
	s_nop 0
	v_writelane_b32 v255, s3, 60
.Lgb_known:
	s_cmp_lg_u32 s3, 1
	s_cbranch_scc1 .Lgb_no
	s_waitcnt vmcnt(0) lgkmcnt(0)
	s_barrier
	s_mov_b64 s[6:7], exec
	v_readlane_b32 s2, v255, 32
	v_readlane_b32 s3, v255, 33
	s_and_b64 s[2:3], s[6:7], s[2:3]
	s_mov_b64 exec, s[2:3]
	s_cbranch_execz .Lgb_wait
	v_readlane_b32 s8, v255, 36
	s_and_b32 s9, s8, 7
	s_lshr_b32 s8, s8, 5
	s_lshl_b32 s8, s8, 3
	s_add_i32 s8, s8, s9
	s_lshl_b32 s8, s8, 6
	s_add_i32 s8, s8, 0x8000
	v_mov_b32_e32 v0, s8
	v_mov_b32_e32 v1, 1
	global_atomic_add v0, v1, s[82:83] sc1
.Lgb_poll:
	v_mov_b32_e32 v1, 0
	global_atomic_add v2, v0, v1, s[82:83] sc0 sc1
	s_waitcnt vmcnt(0)
	v_cmp_gt_u32_e32 vcc, s1, v2
	s_cbranch_vccz .Lgb_done
	s_sleep 1
	s_branch .Lgb_poll

.Lgb_wait:
	s_mov_b64 exec, s[6:7]
	s_mov_b64 s[2:3], 0
	s_waitcnt vmcnt(0) lgkmcnt(0)
	s_barrier
	s_branch .LBB0_2072
